# P5 epilogue (last tile): residual loads of the two ai=1 row batches staged one batch early by LDS-DMA into the wave's own ring slices
# baseline (speedup 1.0000x reference)
; __device__ __forceinline__ u32x4 pack8(const float (&v)[8]) { u32x4 w; w.x = cvtpk(v[0], v[1]); w.y = cvtpk(v[2], v[3]); w.z = cvtpk(v[4], v[5]); w.w = cvtpk(v[6], v[7]); return w; }
; #define LAS __attribute__((address_space(3)))
;     __device__ __forceinline__ void operator()(const pg8::f32x4 (&acc)[2][2][4][2], const pg8::Unit& u, int wr, int wc, int fr, int fq) const {
;         LAS char* xl = (LAS char*)xb + ((wr * 64 + fr) * 8 + wc) * 4; asm volatile("" : "+v"(xl));
;         const int b = u.pm >> 4; const float* mb = e.mod + (size_t)b * NMOD;
; #pragma unroll
;         for (int bj = 0; bj < 2; ++bj) {
;             const int c0 = u.pn * 256 + bj * 128 + wc * 32 + 8 * fq; float g1[8], gm[8];
; #pragma unroll
;             for (int h = 0; h < 2; ++h) { const f32x4 a = *(const f32x4*)(mb + 2 * DM + c0 + 4 * h), sc = *(const f32x4*)(mb + 4 * DM + c0 + 4 * h), ng = *(const f32x4*)(e.n2g + c0 + 4 * h);
; #pragma unroll
;                 for (int i = 0; i < 4; ++i) { g1[4 * h + i] = a[i]; gm[4 * h + i] = ng[i] * (1.0f + sc[i]); } }
; #pragma unroll
;             for (int ai = 0; ai < 2; ++ai) {
;                 f32x4 xa[4], xc[4];
; #pragma unroll
;                 for (int m = 0; m < 4; ++m) { const size_t off = (size_t)(u.pm * 256 + ai * 128 + wr * 64 + m * 16 + fr) * DM + c0; xa[m] = __builtin_nontemporal_load((const f32x4*)(e.x + off)); xc[m] = __builtin_nontemporal_load((const f32x4*)(e.x + off + 4)); }
; #pragma unroll
;                 for (int m = 0; m < 4; ++m) { ACC8(v, ai, bj, m); const size_t off = (size_t)(u.pm * 256 + ai * 128 + wr * 64 + m * 16 + fr) * DM + c0;
;                     float o[8], y[8], s = 0.f;
; #pragma unroll
;                     for (int i = 0; i < 8; ++i) { o[i] = (i < 4 ? xa[m][i & 3] : xc[m][i & 3]) + g1[i] * v[i]; s += o[i] * o[i]; y[i] = o[i] * gm[i]; }
;                     *(f32x4*)(e.out + off) = (f32x4){o[0], o[1], o[2], o[3]}; *(f32x4*)(e.out + off + 4) = (f32x4){o[4], o[5], o[6], o[7]};
;                     *(u32x4*)(e.Y2 + off) = pack8(y);
;                     s += __shfl_xor(s, 16); s += __shfl_xor(s, 32);
;                     if (fq == 0) *(LAS float*)(xl + ((ai * 128 + m * 16) * 8 + bj * 4) * 4) = s; }
.LBB9_668:
	s_cmp_lg_u64 s[6:7], 0
	s_cbranch_scc1 .Lp5o_668
	s_ashr_i32 s2, s30, 4
	s_mul_hi_i32 s3, s2, 0x6000
	s_mulk_i32 s2, 0x6000
	s_add_u32 s2, s48, s2
	s_addc_u32 s3, s49, s3
	s_add_u32 s34, s2, 0x2000
	s_addc_u32 s35, s3, 0
	s_add_u32 s36, s2, 0x4000
	v_lshl_or_b32 v176, s10, 8, v211
	s_addc_u32 s37, s3, 0
	s_lshl_b32 s11, s30, 8
	v_add_u32_e32 v198, s11, v209
	v_ashrrev_i32_e32 v177, 31, v176
	v_readlane_b32 s60, v251, 0
	v_lshlrev_b64 v[128:129], 2, v[176:177]
	v_readlane_b32 s61, v251, 1
	v_readlane_b32 s74, v251, 14
	v_readlane_b32 s75, v251, 15
	v_ashrrev_i32_e32 v199, 31, v198
	v_mov_b32_e32 v218, v212
	v_lshl_add_u64 v[130:131], s[34:35], 0, v[128:129]
	v_lshl_add_u64 v[132:133], s[36:37], 0, v[128:129]
	v_lshl_add_u64 v[178:179], s[74:75], 0, v[128:129]
	v_lshl_add_u64 v[200:201], s[60:61], 0, v[128:129]
	v_lshlrev_b64 v[128:129], 12, v[198:199]
	global_load_dwordx4 v[190:193], v[132:133], off offset:16
	global_load_dwordx4 v[194:197], v[132:133], off
	global_load_dwordx4 v[222:225], v[178:179], off offset:16
	global_load_dwordx4 v[226:229], v[178:179], off
	v_lshl_add_u64 v[182:183], v[200:201], 0, v[128:129]
	global_load_dwordx4 v[230:233], v[182:183], off nt
	global_load_dwordx4 v[132:135], v[130:131], off
	s_nop 0
	global_load_dwordx4 v[128:131], v[130:131], off offset:16
	s_nop 0
	global_load_dwordx4 v[234:237], v[182:183], off offset:16 nt
	v_or_b32_e32 v206, 16, v198
	v_or_b32_e32 v204, 32, v198
	v_or_b32_e32 v202, 48, v198
	v_ashrrev_i32_e32 v207, 31, v206
	v_ashrrev_i32_e32 v205, 31, v204
	v_ashrrev_i32_e32 v203, 31, v202
	v_lshlrev_b64 v[136:137], 12, v[206:207]
	v_lshlrev_b64 v[138:139], 12, v[204:205]
	v_lshlrev_b64 v[140:141], 12, v[202:203]
	v_lshl_add_u64 v[188:189], v[200:201], 0, v[136:137]
	v_lshl_add_u64 v[186:187], v[200:201], 0, v[138:139]
	v_lshl_add_u64 v[184:185], v[200:201], 0, v[140:141]
	global_load_dwordx4 v[152:155], v[188:189], off offset:16 nt
	global_load_dwordx4 v[156:159], v[188:189], off nt
	global_load_dwordx4 v[144:147], v[186:187], off offset:16 nt
	global_load_dwordx4 v[148:151], v[186:187], off nt
	global_load_dwordx4 v[136:139], v[184:185], off offset:16 nt
	global_load_dwordx4 v[140:143], v[184:185], off nt
	v_mbcnt_lo_u32_b32 v249, -1, 0
	v_mbcnt_hi_u32_b32 v249, -1, v249
	v_lshlrev_b32_e32 v249, 4, v249
	v_add_u32_e32 v249, s31, v249
	s_waitcnt vmcnt(14)
	s_mov_b32 s99, 0
	s_mov_b32 s98, 0x80000
	s_add_i32 m0, s31, 0x0
	v_lshl_add_u64 v[240:241], v[182:183], 0, s[98:99]
	global_load_lds_dwordx4 v[240:241], off
	s_mov_b32 s98, 0x80010
	s_add_i32 m0, s31, 0x4000
	v_lshl_add_u64 v[242:243], v[182:183], 0, s[98:99]
	global_load_lds_dwordx4 v[242:243], off
	s_mov_b32 s98, 0x80010
	s_add_i32 m0, s31, 0x8000
	v_lshl_add_u64 v[240:241], v[188:189], 0, s[98:99]
	global_load_lds_dwordx4 v[240:241], off
	s_mov_b32 s98, 0x80000
	s_add_i32 m0, s31, 0xc000
	v_lshl_add_u64 v[242:243], v[188:189], 0, s[98:99]
	global_load_lds_dwordx4 v[242:243], off
	s_mov_b32 s98, 0x80010
	s_add_i32 m0, s31, 0x2000
	v_lshl_add_u64 v[240:241], v[186:187], 0, s[98:99]
	global_load_lds_dwordx4 v[240:241], off
	s_mov_b32 s98, 0x80000
	s_add_i32 m0, s31, 0x6000
	v_lshl_add_u64 v[242:243], v[186:187], 0, s[98:99]
	global_load_lds_dwordx4 v[242:243], off
	s_mov_b32 s98, 0x80010
	s_add_i32 m0, s31, 0xa000
	v_lshl_add_u64 v[240:241], v[184:185], 0, s[98:99]
	global_load_lds_dwordx4 v[240:241], off
	s_mov_b32 s98, 0x80000
	s_add_i32 m0, s31, 0xe000
	v_lshl_add_u64 v[242:243], v[184:185], 0, s[98:99]
	global_load_lds_dwordx4 v[242:243], off
	v_and_b32_e32 v181, 64, v217
	v_xor_b32_e32 v180, 16, v217
	v_add_u32_e32 v181, 64, v181
	v_cmp_lt_i32_e32 vcc, v180, v181
	v_xor_b32_e32 v219, 32, v217
	v_readlane_b32 s62, v251, 2
	v_cndmask_b32_e32 v180, v217, v180, vcc
	v_lshlrev_b32_e32 v220, 2, v180
	v_cmp_lt_i32_e32 vcc, v219, v181
	v_readlane_b32 s63, v251, 3
	v_readlane_b32 s64, v251, 4
	v_cndmask_b32_e32 v181, v217, v219, vcc
	v_lshlrev_b32_e32 v219, 2, v181
	v_lshlrev_b64 v[180:181], 10, v[198:199]
	v_lshl_add_u64 v[238:239], v[180:181], 0, v[176:177]
	v_readlane_b32 s65, v251, 5
	v_readlane_b32 s66, v251, 6
	v_readlane_b32 s67, v251, 7
	v_readlane_b32 s68, v251, 8
	v_readlane_b32 s69, v251, 9
	v_readlane_b32 s70, v251, 10
	v_readlane_b32 s71, v251, 11
	v_readlane_b32 s72, v251, 12
	v_readlane_b32 s73, v251, 13
	s_waitcnt vmcnt(8)
	v_pk_add_f32 v[190:191], v[190:191], 1.0 op_sel_hi:[1,0]
	v_pk_add_f32 v[192:193], v[192:193], 1.0 op_sel_hi:[1,0]
	v_pk_mul_f32 v[190:191], v[222:223], v[190:191]
	v_pk_fma_f32 v[222:223], v[124:125], v[132:133], v[230:231]
	v_pk_mul_f32 v[192:193], v[224:225], v[192:193]
	v_pk_fma_f32 v[224:225], v[126:127], v[134:135], v[232:233]
	v_pk_mul_f32 v[126:127], v[222:223], v[222:223]
	v_pk_mul_f32 v[124:125], v[224:225], v[224:225]
	v_add_f32_e32 v126, v126, v127
	v_pk_fma_f32 v[120:121], v[120:121], v[128:129], v[234:235]
	v_add_f32_e32 v124, v124, v126
	v_pk_mul_f32 v[232:233], v[120:121], v[120:121]
	v_add_f32_e32 v124, v125, v124
	v_pk_fma_f32 v[122:123], v[122:123], v[130:131], v[236:237]
	v_add_f32_e32 v124, v232, v124
	v_pk_mul_f32 v[230:231], v[122:123], v[122:123]
	v_add_f32_e32 v124, v233, v124
	v_add_f32_e32 v124, v230, v124
	v_add_f32_e32 v124, v231, v124
	ds_bpermute_b32 v125, v220, v124
	v_lshl_add_u64 v[126:127], v[238:239], 2, s[88:89]
	v_pk_mul_f32 v[234:235], v[190:191], v[120:121]
	global_store_dwordx4 v[126:127], v[222:225], off
	global_store_dwordx4 v[126:127], v[120:123], off offset:16
	v_pk_add_f32 v[194:195], v[194:195], 1.0 op_sel_hi:[1,0]
	v_pk_add_f32 v[196:197], v[196:197], 1.0 op_sel_hi:[1,0]
	s_waitcnt lgkmcnt(0)
	v_add_f32_e32 v120, v124, v125
	ds_bpermute_b32 v121, v219, v120
	v_pk_mul_f32 v[194:195], v[226:227], v[194:195]
	v_pk_mul_f32 v[196:197], v[228:229], v[196:197]
	v_pk_mul_f32 v[226:227], v[194:195], v[222:223]
	v_pk_mul_f32 v[228:229], v[196:197], v[224:225]
	v_pk_mul_f32 v[236:237], v[192:193], v[122:123]
	v_cvt_pk_bf16_f32 v122, v226, v227
	v_cvt_pk_bf16_f32 v123, v228, v229
	v_cvt_pk_bf16_f32 v124, v234, v235
	v_cvt_pk_bf16_f32 v125, v236, v237
	v_lshl_add_u64 v[222:223], v[238:239], 1, s[16:17]
	global_store_dwordx4 v[222:223], v[122:125], off
	s_and_saveexec_b64 s[2:3], s[0:1]
	s_cbranch_execz .LBB9_670
	s_waitcnt lgkmcnt(0)
	v_add_f32_e32 v120, v120, v121
	ds_write_b32 v218, v120

; __device__ __forceinline__ u32x4 pack8(const float (&v)[8]) { u32x4 w; w.x = cvtpk(v[0], v[1]); w.y = cvtpk(v[2], v[3]); w.z = cvtpk(v[4], v[5]); w.w = cvtpk(v[6], v[7]); return w; }
; #define LAS __attribute__((address_space(3)))
;     __device__ __forceinline__ void operator()(const pg8::f32x4 (&acc)[2][2][4][2], const pg8::Unit& u, int wr, int wc, int fr, int fq) const {
;     ...
;             for (int ai = 0; ai < 2; ++ai) {
;                 f32x4 xa[4], xc[4];
; #pragma unroll
;                 for (int m = 0; m < 4; ++m) { const size_t off = (size_t)(u.pm * 256 + ai * 128 + wr * 64 + m * 16 + fr) * DM + c0; xa[m] = __builtin_nontemporal_load((const f32x4*)(e.x + off)); xc[m] = __builtin_nontemporal_load((const f32x4*)(e.x + off + 4)); }
; #pragma unroll
;                 for (int m = 0; m < 4; ++m) { ACC8(v, ai, bj, m); const size_t off = (size_t)(u.pm * 256 + ai * 128 + wr * 64 + m * 16 + fr) * DM + c0;
;                     float o[8], y[8], s = 0.f;
; #pragma unroll
;                     for (int i = 0; i < 8; ++i) { o[i] = (i < 4 ? xa[m][i & 3] : xc[m][i & 3]) + g1[i] * v[i]; s += o[i] * o[i]; y[i] = o[i] * gm[i]; }
;                     *(f32x4*)(e.out + off) = (f32x4){o[0], o[1], o[2], o[3]}; *(f32x4*)(e.out + off + 4) = (f32x4){o[4], o[5], o[6], o[7]};
;                     *(u32x4*)(e.Y2 + off) = pack8(y);
;                     s += __shfl_xor(s, 16); s += __shfl_xor(s, 32);
;                     if (fq == 0) *(LAS float*)(xl + ((ai * 128 + m * 16) * 8 + bj * 4) * 4) = s; }
.LBB9_676:
	s_or_b64 exec, exec, s[2:3]
	v_add_u32_e32 v138, 0x80, v198
	v_ashrrev_i32_e32 v139, 31, v138
	s_waitcnt lgkmcnt(0)
	v_lshlrev_b64 v[96:97], 12, v[138:139]
	v_lshl_add_u64 v[140:141], v[200:201], 0, v[96:97]
	s_waitcnt vmcnt(12)
	ds_read_b128 v[202:205], v249 offset:0
	ds_read_b128 v[222:225], v249 offset:16384
	v_add_u32_e32 v142, 0x90, v198
	v_add_u32_e32 v158, 0xa0, v198
	v_add_u32_e32 v156, 0xb0, v198
	v_ashrrev_i32_e32 v143, 31, v142
	v_ashrrev_i32_e32 v159, 31, v158
	v_ashrrev_i32_e32 v157, 31, v156
	v_lshlrev_b64 v[96:97], 12, v[142:143]
	v_lshlrev_b64 v[98:99], 12, v[158:159]
	v_lshlrev_b64 v[100:101], 12, v[156:157]
	v_lshl_add_u64 v[154:155], v[200:201], 0, v[96:97]
	v_lshl_add_u64 v[150:151], v[200:201], 0, v[98:99]
	v_lshl_add_u64 v[146:147], v[200:201], 0, v[100:101]
	ds_read_b128 v[112:115], v249 offset:32768
	ds_read_b128 v[116:119], v249 offset:49152
	ds_read_b128 v[104:107], v249 offset:8192
	ds_read_b128 v[108:111], v249 offset:24576
	ds_read_b128 v[96:99], v249 offset:40960
	ds_read_b128 v[100:103], v249 offset:57344
	v_lshlrev_b64 v[138:139], 10, v[138:139]
	v_lshl_add_u64 v[198:199], v[138:139], 0, v[176:177]
	s_waitcnt lgkmcnt(0)
	v_pk_fma_f32 v[92:93], v[92:93], v[132:133], v[202:203]
	v_pk_fma_f32 v[94:95], v[94:95], v[134:135], v[204:205]
	v_pk_mul_f32 v[200:201], v[92:93], v[92:93]
	v_pk_mul_f32 v[148:149], v[94:95], v[94:95]
	v_add_f32_e32 v200, v200, v201
	s_nop 0
	v_pk_fma_f32 v[88:89], v[88:89], v[128:129], v[222:223]
	v_add_f32_e32 v148, v148, v200
	v_pk_mul_f32 v[222:223], v[88:89], v[88:89]
	v_add_f32_e32 v148, v149, v148
	v_pk_fma_f32 v[90:91], v[90:91], v[130:131], v[224:225]
	v_add_f32_e32 v148, v222, v148
	v_pk_mul_f32 v[206:207], v[90:91], v[90:91]
	v_add_f32_e32 v148, v223, v148
	v_add_f32_e32 v148, v206, v148
	v_add_f32_e32 v200, v207, v148
	ds_bpermute_b32 v201, v220, v200
	v_lshl_add_u64 v[148:149], v[198:199], 2, s[88:89]
	v_pk_mul_f32 v[224:225], v[190:191], v[88:89]
	global_store_dwordx4 v[148:149], v[92:95], off
	global_store_dwordx4 v[148:149], v[88:91], off offset:16
	v_pk_mul_f32 v[202:203], v[194:195], v[92:93]
	v_pk_mul_f32 v[204:205], v[196:197], v[94:95]
	s_waitcnt lgkmcnt(0)
	v_add_f32_e32 v88, v200, v201
	ds_bpermute_b32 v89, v219, v88
	v_pk_mul_f32 v[226:227], v[192:193], v[90:91]
	v_cvt_pk_bf16_f32 v90, v202, v203
	v_cvt_pk_bf16_f32 v91, v204, v205
	v_cvt_pk_bf16_f32 v92, v224, v225
	v_cvt_pk_bf16_f32 v93, v226, v227
	v_lshl_add_u64 v[94:95], v[198:199], 1, s[16:17]
	global_store_dwordx4 v[94:95], v[90:93], off
	s_and_saveexec_b64 s[2:3], s[0:1]
	s_cbranch_execz .LBB9_678
	s_waitcnt lgkmcnt(0)
	v_add_f32_e32 v88, v88, v89
	ds_write_b32 v218, v88 offset:4096
.LBB9_678:
	s_or_b64 exec, exec, s[2:3]
	s_nop 0
	v_pk_fma_f32 v[84:85], v[84:85], v[132:133], v[116:117]
	v_pk_fma_f32 v[86:87], v[86:87], v[134:135], v[118:119]
	v_pk_mul_f32 v[90:91], v[84:85], v[84:85]
	s_waitcnt lgkmcnt(0)
	v_pk_mul_f32 v[88:89], v[86:87], v[86:87]
	v_add_f32_e32 v90, v90, v91
	v_pk_fma_f32 v[80:81], v[80:81], v[128:129], v[112:113]
	v_add_f32_e32 v88, v88, v90
	v_pk_fma_f32 v[82:83], v[82:83], v[130:131], v[114:115]
	v_pk_mul_f32 v[114:115], v[80:81], v[80:81]
	v_add_f32_e32 v88, v89, v88
	v_add_f32_e32 v88, v114, v88
	v_pk_mul_f32 v[112:113], v[82:83], v[82:83]
	v_add_f32_e32 v88, v115, v88
	v_add_f32_e32 v88, v112, v88
	v_add_f32_e32 v90, v113, v88
	ds_bpermute_b32 v91, v220, v90
	v_lshlrev_b64 v[142:143], 10, v[142:143]
	v_lshl_add_u64 v[88:89], v[142:143], 0, v[176:177]
	v_lshl_add_u64 v[114:115], v[88:89], 2, s[88:89]
	v_pk_mul_f32 v[116:117], v[190:191], v[80:81]
	global_store_dwordx4 v[114:115], v[84:87], off
	global_store_dwordx4 v[114:115], v[80:83], off offset:16
	v_pk_mul_f32 v[92:93], v[194:195], v[84:85]
	v_pk_mul_f32 v[94:95], v[196:197], v[86:87]
	s_waitcnt lgkmcnt(0)
	v_add_f32_e32 v80, v90, v91
	ds_bpermute_b32 v81, v219, v80
	v_pk_mul_f32 v[118:119], v[192:193], v[82:83]
	v_cvt_pk_bf16_f32 v82, v92, v93
	v_cvt_pk_bf16_f32 v83, v94, v95
	v_cvt_pk_bf16_f32 v84, v116, v117
	v_cvt_pk_bf16_f32 v85, v118, v119
	v_lshl_add_u64 v[86:87], v[88:89], 1, s[16:17]
	global_store_dwordx4 v[86:87], v[82:85], off
	s_and_saveexec_b64 s[2:3], s[0:1]
	s_cbranch_execz .LBB9_680
	s_waitcnt lgkmcnt(0)
	v_add_f32_e32 v80, v80, v81
	ds_write_b32 v218, v80 offset:4608
.LBB9_680:
	s_or_b64 exec, exec, s[2:3]
	s_nop 0
	v_pk_fma_f32 v[76:77], v[76:77], v[132:133], v[108:109]
	v_pk_fma_f32 v[78:79], v[78:79], v[134:135], v[110:111]
	v_pk_mul_f32 v[82:83], v[76:77], v[76:77]
	s_waitcnt lgkmcnt(0)
	v_pk_mul_f32 v[80:81], v[78:79], v[78:79]
	v_add_f32_e32 v82, v82, v83
	v_pk_fma_f32 v[72:73], v[72:73], v[128:129], v[104:105]
	v_add_f32_e32 v80, v80, v82
	v_pk_mul_f32 v[90:91], v[72:73], v[72:73]
	v_add_f32_e32 v80, v81, v80
	v_pk_fma_f32 v[74:75], v[74:75], v[130:131], v[106:107]
	v_add_f32_e32 v80, v90, v80
	v_pk_mul_f32 v[88:89], v[74:75], v[74:75]
	v_add_f32_e32 v80, v91, v80
	v_add_f32_e32 v80, v88, v80
	v_add_f32_e32 v82, v89, v80
	ds_bpermute_b32 v83, v220, v82
	v_lshlrev_b64 v[112:113], 10, v[158:159]
	v_lshl_add_u64 v[80:81], v[112:113], 0, v[176:177]
	v_lshl_add_u64 v[106:107], v[80:81], 2, s[88:89]
	v_pk_mul_f32 v[92:93], v[190:191], v[72:73]
	global_store_dwordx4 v[106:107], v[76:79], off
	global_store_dwordx4 v[106:107], v[72:75], off offset:16
	v_pk_mul_f32 v[84:85], v[194:195], v[76:77]
	v_pk_mul_f32 v[86:87], v[196:197], v[78:79]
	s_waitcnt lgkmcnt(0)
	v_add_f32_e32 v72, v82, v83
	ds_bpermute_b32 v73, v219, v72
	v_pk_mul_f32 v[94:95], v[192:193], v[74:75]
	v_cvt_pk_bf16_f32 v74, v84, v85
	v_cvt_pk_bf16_f32 v75, v86, v87
	v_cvt_pk_bf16_f32 v76, v92, v93
	v_cvt_pk_bf16_f32 v77, v94, v95
	v_lshl_add_u64 v[78:79], v[80:81], 1, s[16:17]
	global_store_dwordx4 v[78:79], v[74:77], off
	s_and_saveexec_b64 s[2:3], s[0:1]
	s_cbranch_execz .LBB9_682
	s_waitcnt lgkmcnt(0)
	v_add_f32_e32 v72, v72, v73
	ds_write_b32 v218, v72 offset:5120
; __device__ __forceinline__ u32x4 pack8(const float (&v)[8]) { u32x4 w; w.x = cvtpk(v[0], v[1]); w.y = cvtpk(v[2], v[3]); w.z = cvtpk(v[4], v[5]); w.w = cvtpk(v[6], v[7]); return w; }
; #define LAS __attribute__((address_space(3)))
;     __device__ __forceinline__ void operator()(const pg8::f32x4 (&acc)[2][2][4][2], const pg8::Unit& u, int wr, int wc, int fr, int fq) const {
;     ...
;             for (int ai = 0; ai < 2; ++ai) {
;                 f32x4 xa[4], xc[4];
; #pragma unroll
;                 for (int m = 0; m < 4; ++m) { const size_t off = (size_t)(u.pm * 256 + ai * 128 + wr * 64 + m * 16 + fr) * DM + c0; xa[m] = __builtin_nontemporal_load((const f32x4*)(e.x + off)); xc[m] = __builtin_nontemporal_load((const f32x4*)(e.x + off + 4)); }
; #pragma unroll
;                 for (int m = 0; m < 4; ++m) { ACC8(v, ai, bj, m); const size_t off = (size_t)(u.pm * 256 + ai * 128 + wr * 64 + m * 16 + fr) * DM + c0;
;                     float o[8], y[8], s = 0.f;
; #pragma unroll
;                     for (int i = 0; i < 8; ++i) { o[i] = (i < 4 ? xa[m][i & 3] : xc[m][i & 3]) + g1[i] * v[i]; s += o[i] * o[i]; y[i] = o[i] * gm[i]; }
;                     *(f32x4*)(e.out + off) = (f32x4){o[0], o[1], o[2], o[3]}; *(f32x4*)(e.out + off + 4) = (f32x4){o[4], o[5], o[6], o[7]};
;                     *(u32x4*)(e.Y2 + off) = pack8(y);
;                     s += __shfl_xor(s, 16); s += __shfl_xor(s, 32);
;                     if (fq == 0) *(LAS float*)(xl + ((ai * 128 + m * 16) * 8 + bj * 4) * 4) = s; }
.LBB9_682:
	s_or_b64 exec, exec, s[2:3]
	s_nop 0
	v_pk_fma_f32 v[68:69], v[68:69], v[132:133], v[100:101]
	v_pk_fma_f32 v[70:71], v[70:71], v[134:135], v[102:103]
	v_pk_mul_f32 v[74:75], v[68:69], v[68:69]
	s_waitcnt lgkmcnt(0)
	v_pk_mul_f32 v[72:73], v[70:71], v[70:71]
	v_add_f32_e32 v74, v74, v75
	v_pk_fma_f32 v[64:65], v[64:65], v[128:129], v[96:97]
	v_add_f32_e32 v72, v72, v74
	v_pk_mul_f32 v[82:83], v[64:65], v[64:65]
	v_add_f32_e32 v72, v73, v72
	v_pk_fma_f32 v[66:67], v[66:67], v[130:131], v[98:99]
	v_add_f32_e32 v72, v82, v72
	v_pk_mul_f32 v[80:81], v[66:67], v[66:67]
	v_add_f32_e32 v72, v83, v72
	v_add_f32_e32 v72, v80, v72
	v_add_f32_e32 v74, v81, v72
	ds_bpermute_b32 v75, v220, v74
	v_lshlrev_b64 v[104:105], 10, v[156:157]
	v_lshl_add_u64 v[72:73], v[104:105], 0, v[176:177]
	v_lshl_add_u64 v[96:97], v[72:73], 2, s[88:89]
	v_pk_mul_f32 v[84:85], v[190:191], v[64:65]
	global_store_dwordx4 v[96:97], v[68:71], off
	global_store_dwordx4 v[96:97], v[64:67], off offset:16
	v_pk_mul_f32 v[76:77], v[194:195], v[68:69]
	v_pk_mul_f32 v[78:79], v[196:197], v[70:71]
	s_waitcnt lgkmcnt(0)
	v_add_f32_e32 v64, v74, v75
	ds_bpermute_b32 v65, v219, v64
	v_pk_mul_f32 v[86:87], v[192:193], v[66:67]
	v_cvt_pk_bf16_f32 v66, v76, v77
	v_cvt_pk_bf16_f32 v67, v78, v79
	v_cvt_pk_bf16_f32 v68, v84, v85
	v_cvt_pk_bf16_f32 v69, v86, v87
	v_lshl_add_u64 v[70:71], v[72:73], 1, s[16:17]
	global_store_dwordx4 v[70:71], v[66:69], off
	s_and_saveexec_b64 s[2:3], s[0:1]
	s_cbranch_execz .LBB9_684
	s_waitcnt lgkmcnt(0)
	v_add_f32_e32 v64, v64, v65
	ds_write_b32 v218, v64 offset:5632
.LBB9_684:
	s_or_b64 exec, exec, s[2:3]
	v_or_b32_e32 v98, 0x80, v176
	v_ashrrev_i32_e32 v99, 31, v98
	s_waitcnt lgkmcnt(0)
	v_lshlrev_b64 v[64:65], 2, v[98:99]
	v_lshl_add_u64 v[66:67], s[36:37], 0, v[64:65]
	global_load_dwordx4 v[100:103], v[66:67], off
	global_load_dwordx4 v[108:111], v[66:67], off offset:16
	v_lshl_add_u64 v[68:69], s[34:35], 0, v[64:65]
	global_load_dwordx4 v[64:67], v[68:69], off
	global_load_dwordx4 v[116:119], v[182:183], off offset:512 nt
	global_load_dwordx4 v[128:131], v[182:183], off offset:528 nt
	s_nop 0
	global_load_dwordx4 v[68:71], v[68:69], off offset:16
	s_nop 0
	global_load_dwordx4 v[132:135], v[178:179], off offset:512
	global_load_dwordx4 v[156:159], v[178:179], off offset:528
	global_load_dwordx4 v[88:91], v[188:189], off offset:528 nt
	global_load_dwordx4 v[92:95], v[188:189], off offset:512 nt
	global_load_dwordx4 v[80:83], v[186:187], off offset:528 nt
	global_load_dwordx4 v[84:87], v[186:187], off offset:512 nt
	global_load_dwordx4 v[72:75], v[184:185], off offset:528 nt
	global_load_dwordx4 v[76:79], v[184:185], off offset:512 nt
	s_mov_b32 s99, 0
	s_mov_b32 s98, 0x80200
	s_add_i32 m0, s31, 0x0
	v_lshl_add_u64 v[240:241], v[182:183], 0, s[98:99]
	global_load_lds_dwordx4 v[240:241], off
	s_mov_b32 s98, 0x80210
	s_add_i32 m0, s31, 0x4000
	v_lshl_add_u64 v[242:243], v[182:183], 0, s[98:99]
	global_load_lds_dwordx4 v[242:243], off
	s_mov_b32 s98, 0x80210
	s_add_i32 m0, s31, 0x8000
	v_lshl_add_u64 v[240:241], v[188:189], 0, s[98:99]
	global_load_lds_dwordx4 v[240:241], off
	s_mov_b32 s98, 0x80200
	s_add_i32 m0, s31, 0xc000
	v_lshl_add_u64 v[242:243], v[188:189], 0, s[98:99]
	global_load_lds_dwordx4 v[242:243], off
	s_mov_b32 s98, 0x80210
	s_add_i32 m0, s31, 0x2000
	v_lshl_add_u64 v[240:241], v[186:187], 0, s[98:99]
	global_load_lds_dwordx4 v[240:241], off
	s_mov_b32 s98, 0x80200
	s_add_i32 m0, s31, 0x6000
	v_lshl_add_u64 v[242:243], v[186:187], 0, s[98:99]
	global_load_lds_dwordx4 v[242:243], off
	s_mov_b32 s98, 0x80210
	s_add_i32 m0, s31, 0xa000
	v_lshl_add_u64 v[240:241], v[184:185], 0, s[98:99]
	global_load_lds_dwordx4 v[240:241], off
	s_mov_b32 s98, 0x80200
	s_add_i32 m0, s31, 0xe000
	v_lshl_add_u64 v[242:243], v[184:185], 0, s[98:99]
	global_load_lds_dwordx4 v[242:243], off
	s_waitcnt vmcnt(21)
	v_pk_add_f32 v[176:177], v[100:101], 1.0 op_sel_hi:[1,0]
	s_waitcnt vmcnt(18)
	v_pk_fma_f32 v[100:101], v[60:61], v[64:65], v[116:117]
	v_pk_add_f32 v[178:179], v[102:103], 1.0 op_sel_hi:[1,0]
	v_pk_fma_f32 v[102:103], v[62:63], v[66:67], v[118:119]
	v_pk_mul_f32 v[118:119], v[100:101], v[100:101]
	v_pk_mul_f32 v[116:117], v[102:103], v[102:103]
	v_add_f32_e32 v118, v118, v119
	v_pk_add_f32 v[182:183], v[108:109], 1.0 op_sel_hi:[1,0]
	s_waitcnt vmcnt(16)
	v_pk_fma_f32 v[108:109], v[56:57], v[68:69], v[128:129]
	v_add_f32_e32 v116, v116, v118
	v_pk_add_f32 v[184:185], v[110:111], 1.0 op_sel_hi:[1,0]
	v_pk_fma_f32 v[110:111], v[58:59], v[70:71], v[130:131]
	v_pk_mul_f32 v[130:131], v[108:109], v[108:109]
	v_add_f32_e32 v116, v117, v116
	v_add_f32_e32 v116, v130, v116
	v_pk_mul_f32 v[128:129], v[110:111], v[110:111]
	v_add_f32_e32 v116, v131, v116
	v_add_f32_e32 v116, v128, v116
	v_add_f32_e32 v118, v129, v116
	ds_bpermute_b32 v119, v220, v118
	s_waitcnt vmcnt(15)
	v_pk_mul_f32 v[60:61], v[132:133], v[176:177]
	global_store_dwordx4 v[126:127], v[100:103], off offset:512
	global_store_dwordx4 v[126:127], v[108:111], off offset:528
	v_pk_mul_f32 v[132:133], v[60:61], v[100:101]
	v_pk_mul_f32 v[62:63], v[134:135], v[178:179]
	s_waitcnt lgkmcnt(0)
	v_add_f32_e32 v100, v118, v119
	ds_bpermute_b32 v101, v219, v100
	s_waitcnt vmcnt(16)
	v_pk_mul_f32 v[56:57], v[156:157], v[182:183]
	v_pk_mul_f32 v[58:59], v[158:159], v[184:185]
	v_pk_mul_f32 v[134:135], v[62:63], v[102:103]
	v_pk_mul_f32 v[156:157], v[56:57], v[108:109]
	v_pk_mul_f32 v[158:159], v[58:59], v[110:111]
	v_lshl_add_u64 v[116:117], v[180:181], 0, v[98:99]
	v_cvt_pk_bf16_f32 v108, v132, v133
	v_cvt_pk_bf16_f32 v109, v134, v135
	v_cvt_pk_bf16_f32 v110, v156, v157
	v_cvt_pk_bf16_f32 v111, v158, v159
	v_lshl_add_u64 v[102:103], v[116:117], 1, s[16:17]
	global_store_dwordx4 v[102:103], v[108:111], off
	s_and_saveexec_b64 s[2:3], s[0:1]
	s_cbranch_execz .LBB9_686
	s_waitcnt lgkmcnt(0)
	v_add_f32_e32 v100, v100, v101
	ds_write_b32 v218, v100 offset:16
; __device__ __forceinline__ u32x4 pack8(const float (&v)[8]) { u32x4 w; w.x = cvtpk(v[0], v[1]); w.y = cvtpk(v[2], v[3]); w.z = cvtpk(v[4], v[5]); w.w = cvtpk(v[6], v[7]); return w; }
; #define LAS __attribute__((address_space(3)))
;     __device__ __forceinline__ void operator()(const pg8::f32x4 (&acc)[2][2][4][2], const pg8::Unit& u, int wr, int wc, int fr, int fq) const {
;     ...
;             for (int ai = 0; ai < 2; ++ai) {
;                 f32x4 xa[4], xc[4];
; #pragma unroll
;                 for (int m = 0; m < 4; ++m) { const size_t off = (size_t)(u.pm * 256 + ai * 128 + wr * 64 + m * 16 + fr) * DM + c0; xa[m] = __builtin_nontemporal_load((const f32x4*)(e.x + off)); xc[m] = __builtin_nontemporal_load((const f32x4*)(e.x + off + 4)); }
; #pragma unroll
;                 for (int m = 0; m < 4; ++m) { ACC8(v, ai, bj, m); const size_t off = (size_t)(u.pm * 256 + ai * 128 + wr * 64 + m * 16 + fr) * DM + c0;
;                     float o[8], y[8], s = 0.f;
; #pragma unroll
;                     for (int i = 0; i < 8; ++i) { o[i] = (i < 4 ? xa[m][i & 3] : xc[m][i & 3]) + g1[i] * v[i]; s += o[i] * o[i]; y[i] = o[i] * gm[i]; }
;                     *(f32x4*)(e.out + off) = (f32x4){o[0], o[1], o[2], o[3]}; *(f32x4*)(e.out + off + 4) = (f32x4){o[4], o[5], o[6], o[7]};
;                     *(u32x4*)(e.Y2 + off) = pack8(y);
;                     s += __shfl_xor(s, 16); s += __shfl_xor(s, 32);
;                     if (fq == 0) *(LAS float*)(xl + ((ai * 128 + m * 16) * 8 + bj * 4) * 4) = s; }
.LBB9_686:
	s_or_b64 exec, exec, s[2:3]
	s_waitcnt vmcnt(15)
	v_pk_fma_f32 v[52:53], v[52:53], v[64:65], v[92:93]
	v_pk_fma_f32 v[54:55], v[54:55], v[66:67], v[94:95]
	v_pk_mul_f32 v[94:95], v[52:53], v[52:53]
	v_pk_mul_f32 v[92:93], v[54:55], v[54:55]
	v_add_f32_e32 v94, v94, v95
	v_pk_fma_f32 v[48:49], v[48:49], v[68:69], v[88:89]
	v_add_f32_e32 v92, v92, v94
	v_pk_fma_f32 v[50:51], v[50:51], v[70:71], v[90:91]
	v_pk_mul_f32 v[90:91], v[48:49], v[48:49]
	v_add_f32_e32 v92, v93, v92
	v_add_f32_e32 v90, v90, v92
	v_pk_mul_f32 v[88:89], v[50:51], v[50:51]
	v_add_f32_e32 v90, v91, v90
	v_add_f32_e32 v88, v88, v90
	v_add_f32_e32 v90, v89, v88
	ds_bpermute_b32 v91, v220, v90
	v_pk_mul_f32 v[108:109], v[56:57], v[48:49]
	global_store_dwordx4 v[152:153], v[52:55], off offset:512
	global_store_dwordx4 v[152:153], v[48:51], off offset:528
	s_waitcnt lgkmcnt(1)
	v_pk_mul_f32 v[100:101], v[60:61], v[52:53]
	v_pk_mul_f32 v[102:103], v[62:63], v[54:55]
	s_waitcnt lgkmcnt(0)
	v_add_f32_e32 v48, v90, v91
	ds_bpermute_b32 v49, v219, v48
	v_pk_mul_f32 v[110:111], v[58:59], v[50:51]
	v_lshl_add_u64 v[88:89], v[122:123], 0, v[98:99]
	v_cvt_pk_bf16_f32 v50, v100, v101
	v_cvt_pk_bf16_f32 v51, v102, v103
	v_cvt_pk_bf16_f32 v52, v108, v109
	v_cvt_pk_bf16_f32 v53, v110, v111
	v_lshl_add_u64 v[54:55], v[88:89], 1, s[16:17]
	global_store_dwordx4 v[54:55], v[50:53], off
	s_and_saveexec_b64 s[2:3], s[0:1]
	s_cbranch_execz .LBB9_688
	s_waitcnt lgkmcnt(0)
	v_add_f32_e32 v48, v48, v49
	ds_write_b32 v218, v48 offset:528
.LBB9_688:
	s_or_b64 exec, exec, s[2:3]
	s_waitcnt vmcnt(16)
	v_pk_fma_f32 v[44:45], v[44:45], v[64:65], v[84:85]
	v_pk_fma_f32 v[46:47], v[46:47], v[66:67], v[86:87]
	v_pk_mul_f32 v[50:51], v[44:45], v[44:45]
	s_waitcnt lgkmcnt(0)
	v_pk_mul_f32 v[48:49], v[46:47], v[46:47]
	v_add_f32_e32 v50, v50, v51
	v_pk_fma_f32 v[40:41], v[40:41], v[68:69], v[80:81]
	v_add_f32_e32 v48, v48, v50
	v_pk_fma_f32 v[42:43], v[42:43], v[70:71], v[82:83]
	v_pk_mul_f32 v[82:83], v[40:41], v[40:41]
	v_add_f32_e32 v48, v49, v48
	v_add_f32_e32 v48, v82, v48
	v_pk_mul_f32 v[80:81], v[42:43], v[42:43]
	v_add_f32_e32 v48, v83, v48
	v_add_f32_e32 v48, v80, v48
	v_add_f32_e32 v50, v81, v48
	ds_bpermute_b32 v51, v220, v50
	v_pk_mul_f32 v[84:85], v[56:57], v[40:41]
	global_store_dwordx4 v[144:145], v[44:47], off offset:512
	global_store_dwordx4 v[144:145], v[40:43], off offset:528
	v_pk_mul_f32 v[52:53], v[60:61], v[44:45]
	v_pk_mul_f32 v[54:55], v[62:63], v[46:47]
	s_waitcnt lgkmcnt(0)
	v_add_f32_e32 v40, v50, v51
	ds_bpermute_b32 v41, v219, v40
	v_pk_mul_f32 v[86:87], v[58:59], v[42:43]
	v_lshl_add_u64 v[48:49], v[120:121], 0, v[98:99]
	v_cvt_pk_bf16_f32 v42, v52, v53
	v_cvt_pk_bf16_f32 v43, v54, v55
	v_cvt_pk_bf16_f32 v44, v84, v85
	v_cvt_pk_bf16_f32 v45, v86, v87
	v_lshl_add_u64 v[46:47], v[48:49], 1, s[16:17]
	global_store_dwordx4 v[46:47], v[42:45], off
	s_and_saveexec_b64 s[2:3], s[0:1]
	s_cbranch_execz .LBB9_690
	s_waitcnt lgkmcnt(0)
	v_add_f32_e32 v40, v40, v41
	ds_write_b32 v218, v40 offset:1040
.LBB9_690:
	s_or_b64 exec, exec, s[2:3]
	s_waitcnt vmcnt(17)
	v_pk_fma_f32 v[36:37], v[36:37], v[64:65], v[76:77]
	v_pk_fma_f32 v[38:39], v[38:39], v[66:67], v[78:79]
	v_pk_mul_f32 v[42:43], v[36:37], v[36:37]
	s_waitcnt lgkmcnt(0)
	v_pk_mul_f32 v[40:41], v[38:39], v[38:39]
	v_add_f32_e32 v42, v42, v43
	v_pk_fma_f32 v[32:33], v[32:33], v[68:69], v[72:73]
	v_add_f32_e32 v40, v40, v42
	v_pk_mul_f32 v[50:51], v[32:33], v[32:33]
	v_add_f32_e32 v40, v41, v40
	v_pk_fma_f32 v[34:35], v[34:35], v[70:71], v[74:75]
	v_add_f32_e32 v40, v50, v40
	v_pk_mul_f32 v[48:49], v[34:35], v[34:35]
	v_add_f32_e32 v40, v51, v40
	v_add_f32_e32 v40, v48, v40
	v_add_f32_e32 v42, v49, v40
	ds_bpermute_b32 v43, v220, v42
	v_pk_mul_f32 v[52:53], v[56:57], v[32:33]
	global_store_dwordx4 v[136:137], v[36:39], off offset:512
	global_store_dwordx4 v[136:137], v[32:35], off offset:528
	v_pk_mul_f32 v[44:45], v[60:61], v[36:37]
	v_pk_mul_f32 v[46:47], v[62:63], v[38:39]
	s_waitcnt lgkmcnt(0)
	v_add_f32_e32 v32, v42, v43
	ds_bpermute_b32 v33, v219, v32
	v_pk_mul_f32 v[54:55], v[58:59], v[34:35]
	v_lshl_add_u64 v[40:41], v[124:125], 0, v[98:99]
	v_cvt_pk_bf16_f32 v34, v44, v45
	v_cvt_pk_bf16_f32 v35, v46, v47
	v_cvt_pk_bf16_f32 v36, v52, v53
	v_cvt_pk_bf16_f32 v37, v54, v55
	v_lshl_add_u64 v[38:39], v[40:41], 1, s[16:17]
	global_store_dwordx4 v[38:39], v[34:37], off
	s_and_saveexec_b64 s[2:3], s[0:1]
	s_cbranch_execz .LBB9_692
	s_waitcnt lgkmcnt(0)
	v_add_f32_e32 v32, v32, v33
	ds_write_b32 v218, v32 offset:1552
; __device__ __forceinline__ u32x4 pack8(const float (&v)[8]) { u32x4 w; w.x = cvtpk(v[0], v[1]); w.y = cvtpk(v[2], v[3]); w.z = cvtpk(v[4], v[5]); w.w = cvtpk(v[6], v[7]); return w; }
; #define LAS __attribute__((address_space(3)))
;     __device__ __forceinline__ void operator()(const pg8::f32x4 (&acc)[2][2][4][2], const pg8::Unit& u, int wr, int wc, int fr, int fq) const {
;     ...
;             for (int ai = 0; ai < 2; ++ai) {
;                 f32x4 xa[4], xc[4];
; #pragma unroll
;                 for (int m = 0; m < 4; ++m) { const size_t off = (size_t)(u.pm * 256 + ai * 128 + wr * 64 + m * 16 + fr) * DM + c0; xa[m] = __builtin_nontemporal_load((const f32x4*)(e.x + off)); xc[m] = __builtin_nontemporal_load((const f32x4*)(e.x + off + 4)); }
; #pragma unroll
;                 for (int m = 0; m < 4; ++m) { ACC8(v, ai, bj, m); const size_t off = (size_t)(u.pm * 256 + ai * 128 + wr * 64 + m * 16 + fr) * DM + c0;
;                     float o[8], y[8], s = 0.f;
; #pragma unroll
;                     for (int i = 0; i < 8; ++i) { o[i] = (i < 4 ? xa[m][i & 3] : xc[m][i & 3]) + g1[i] * v[i]; s += o[i] * o[i]; y[i] = o[i] * gm[i]; }
;                     *(f32x4*)(e.out + off) = (f32x4){o[0], o[1], o[2], o[3]}; *(f32x4*)(e.out + off + 4) = (f32x4){o[4], o[5], o[6], o[7]};
;                     *(u32x4*)(e.Y2 + off) = pack8(y);
;                     s += __shfl_xor(s, 16); s += __shfl_xor(s, 32);
;                     if (fq == 0) *(LAS float*)(xl + ((ai * 128 + m * 16) * 8 + bj * 4) * 4) = s; }
.LBB9_692:
	s_or_b64 exec, exec, s[2:3]
	s_waitcnt vmcnt(12)
	ds_read_b128 v[72:75], v249 offset:0
	ds_read_b128 v[76:79], v249 offset:16384
	ds_read_b128 v[48:51], v249 offset:32768
	ds_read_b128 v[52:55], v249 offset:49152
	ds_read_b128 v[40:43], v249 offset:8192
	ds_read_b128 v[44:47], v249 offset:24576
	s_waitcnt lgkmcnt(0)
	ds_read_b128 v[32:35], v249 offset:40960
	ds_read_b128 v[36:39], v249 offset:57344
	s_waitcnt lgkmcnt(0)
	v_pk_fma_f32 v[28:29], v[28:29], v[64:65], v[72:73]
	v_pk_fma_f32 v[30:31], v[30:31], v[66:67], v[74:75]
	v_pk_mul_f32 v[74:75], v[28:29], v[28:29]
	v_pk_mul_f32 v[72:73], v[30:31], v[30:31]
	v_add_f32_e32 v74, v74, v75
	s_nop 0
	v_pk_fma_f32 v[24:25], v[24:25], v[68:69], v[76:77]
	v_add_f32_e32 v72, v72, v74
	v_pk_mul_f32 v[82:83], v[24:25], v[24:25]
	v_add_f32_e32 v72, v73, v72
	v_pk_fma_f32 v[26:27], v[26:27], v[70:71], v[78:79]
	v_add_f32_e32 v72, v82, v72
	v_pk_mul_f32 v[80:81], v[26:27], v[26:27]
	v_add_f32_e32 v72, v83, v72
	v_add_f32_e32 v72, v80, v72
	v_add_f32_e32 v74, v81, v72
	ds_bpermute_b32 v75, v220, v74
	v_pk_mul_f32 v[84:85], v[56:57], v[24:25]
	global_store_dwordx4 v[148:149], v[28:31], off offset:512
	global_store_dwordx4 v[148:149], v[24:27], off offset:528
	v_pk_mul_f32 v[76:77], v[60:61], v[28:29]
	v_pk_mul_f32 v[78:79], v[62:63], v[30:31]
	s_waitcnt lgkmcnt(0)
	v_add_f32_e32 v24, v74, v75
	ds_bpermute_b32 v25, v219, v24
	v_pk_mul_f32 v[86:87], v[58:59], v[26:27]
	v_lshl_add_u64 v[72:73], v[138:139], 0, v[98:99]
	v_cvt_pk_bf16_f32 v26, v76, v77
	v_cvt_pk_bf16_f32 v27, v78, v79
	v_cvt_pk_bf16_f32 v28, v84, v85
	v_cvt_pk_bf16_f32 v29, v86, v87
	v_lshl_add_u64 v[30:31], v[72:73], 1, s[16:17]
	global_store_dwordx4 v[30:31], v[26:29], off
	s_and_saveexec_b64 s[2:3], s[0:1]
	s_cbranch_execz .LBB9_694
	s_waitcnt lgkmcnt(0)
	v_add_f32_e32 v24, v24, v25
	ds_write_b32 v218, v24 offset:4112
.LBB9_694:
	s_or_b64 exec, exec, s[2:3]
	s_nop 0
	v_pk_fma_f32 v[20:21], v[20:21], v[64:65], v[52:53]
	v_pk_fma_f32 v[22:23], v[22:23], v[66:67], v[54:55]
	v_pk_mul_f32 v[26:27], v[20:21], v[20:21]
	s_waitcnt lgkmcnt(0)
	v_pk_mul_f32 v[24:25], v[22:23], v[22:23]
	v_add_f32_e32 v26, v26, v27
	v_pk_fma_f32 v[16:17], v[16:17], v[68:69], v[48:49]
	v_add_f32_e32 v24, v24, v26
	v_pk_fma_f32 v[18:19], v[18:19], v[70:71], v[50:51]
	v_pk_mul_f32 v[50:51], v[16:17], v[16:17]
	v_add_f32_e32 v24, v25, v24
	v_add_f32_e32 v24, v50, v24
	v_pk_mul_f32 v[48:49], v[18:19], v[18:19]
	v_add_f32_e32 v24, v51, v24
	v_add_f32_e32 v24, v48, v24
	v_add_f32_e32 v26, v49, v24
	ds_bpermute_b32 v27, v220, v26
	v_pk_mul_f32 v[52:53], v[56:57], v[16:17]
	global_store_dwordx4 v[114:115], v[20:23], off offset:512
	global_store_dwordx4 v[114:115], v[16:19], off offset:528
	v_pk_mul_f32 v[28:29], v[60:61], v[20:21]
	v_pk_mul_f32 v[30:31], v[62:63], v[22:23]
	s_waitcnt lgkmcnt(0)
	v_add_f32_e32 v16, v26, v27
	ds_bpermute_b32 v17, v219, v16
	v_pk_mul_f32 v[54:55], v[58:59], v[18:19]
	v_lshl_add_u64 v[24:25], v[142:143], 0, v[98:99]
	v_cvt_pk_bf16_f32 v18, v28, v29
	v_cvt_pk_bf16_f32 v19, v30, v31
	v_cvt_pk_bf16_f32 v20, v52, v53
	v_cvt_pk_bf16_f32 v21, v54, v55
	v_lshl_add_u64 v[22:23], v[24:25], 1, s[16:17]
	global_store_dwordx4 v[22:23], v[18:21], off
	s_and_saveexec_b64 s[2:3], s[0:1]
	s_cbranch_execz .LBB9_696
	s_waitcnt lgkmcnt(0)
	v_add_f32_e32 v16, v16, v17
	ds_write_b32 v218, v16 offset:4624
.LBB9_696:
	s_or_b64 exec, exec, s[2:3]
	s_nop 0
	v_pk_fma_f32 v[12:13], v[12:13], v[64:65], v[44:45]
	v_pk_fma_f32 v[14:15], v[14:15], v[66:67], v[46:47]
	v_pk_mul_f32 v[18:19], v[12:13], v[12:13]
	s_waitcnt lgkmcnt(0)
	v_pk_mul_f32 v[16:17], v[14:15], v[14:15]
	v_add_f32_e32 v18, v18, v19
	v_pk_fma_f32 v[8:9], v[8:9], v[68:69], v[40:41]
	v_add_f32_e32 v16, v16, v18
	v_pk_mul_f32 v[26:27], v[8:9], v[8:9]
	v_add_f32_e32 v16, v17, v16
	v_pk_fma_f32 v[10:11], v[10:11], v[70:71], v[42:43]
	v_add_f32_e32 v16, v26, v16
	v_pk_mul_f32 v[24:25], v[10:11], v[10:11]
	v_add_f32_e32 v16, v27, v16
	v_add_f32_e32 v16, v24, v16
	v_add_f32_e32 v18, v25, v16
	ds_bpermute_b32 v19, v220, v18
	v_pk_mul_f32 v[28:29], v[56:57], v[8:9]
	global_store_dwordx4 v[106:107], v[12:15], off offset:512
	global_store_dwordx4 v[106:107], v[8:11], off offset:528
	v_pk_mul_f32 v[20:21], v[60:61], v[12:13]
	v_pk_mul_f32 v[22:23], v[62:63], v[14:15]
	s_waitcnt lgkmcnt(0)
	v_add_f32_e32 v8, v18, v19
	ds_bpermute_b32 v9, v219, v8
	v_pk_mul_f32 v[30:31], v[58:59], v[10:11]
	v_lshl_add_u64 v[16:17], v[112:113], 0, v[98:99]
	v_cvt_pk_bf16_f32 v10, v20, v21
	v_cvt_pk_bf16_f32 v11, v22, v23
	v_cvt_pk_bf16_f32 v12, v28, v29
	v_cvt_pk_bf16_f32 v13, v30, v31
	v_lshl_add_u64 v[14:15], v[16:17], 1, s[16:17]
	global_store_dwordx4 v[14:15], v[10:13], off
	s_and_saveexec_b64 s[2:3], s[0:1]
	s_cbranch_execz .LBB9_698
	s_waitcnt lgkmcnt(0)
	v_add_f32_e32 v8, v8, v9
	ds_write_b32 v218, v8 offset:5136
.LBB9_698:
	s_or_b64 exec, exec, s[2:3]
	s_nop 0
	v_pk_fma_f32 v[4:5], v[4:5], v[64:65], v[36:37]
	v_pk_fma_f32 v[6:7], v[6:7], v[66:67], v[38:39]
	v_pk_mul_f32 v[10:11], v[4:5], v[4:5]
	s_waitcnt lgkmcnt(0)
	v_pk_mul_f32 v[8:9], v[6:7], v[6:7]
	v_add_f32_e32 v10, v10, v11
	v_pk_fma_f32 v[0:1], v[0:1], v[68:69], v[32:33]
	v_add_f32_e32 v8, v8, v10
	v_pk_mul_f32 v[18:19], v[0:1], v[0:1]
	v_add_f32_e32 v8, v9, v8
	v_pk_fma_f32 v[2:3], v[2:3], v[70:71], v[34:35]
	v_add_f32_e32 v8, v18, v8
	v_pk_mul_f32 v[16:17], v[2:3], v[2:3]
	v_add_f32_e32 v8, v19, v8
	v_add_f32_e32 v8, v16, v8
	v_add_f32_e32 v10, v17, v8
	ds_bpermute_b32 v11, v220, v10
	v_pk_mul_f32 v[20:21], v[56:57], v[0:1]
	global_store_dwordx4 v[96:97], v[4:7], off offset:512
	global_store_dwordx4 v[96:97], v[0:3], off offset:528
	v_pk_mul_f32 v[12:13], v[60:61], v[4:5]
	v_pk_mul_f32 v[14:15], v[62:63], v[6:7]
	s_waitcnt lgkmcnt(0)
	v_add_f32_e32 v0, v10, v11
	ds_bpermute_b32 v1, v219, v0
	v_pk_mul_f32 v[22:23], v[58:59], v[2:3]
	v_lshl_add_u64 v[8:9], v[104:105], 0, v[98:99]
	v_cvt_pk_bf16_f32 v2, v12, v13
	v_cvt_pk_bf16_f32 v3, v14, v15
	v_cvt_pk_bf16_f32 v4, v20, v21
	v_cvt_pk_bf16_f32 v5, v22, v23
	v_lshl_add_u64 v[6:7], v[8:9], 1, s[16:17]
	global_store_dwordx4 v[6:7], v[2:5], off
	s_and_saveexec_b64 s[2:3], s[0:1]
	s_cbranch_execz .LBB9_700
	s_waitcnt lgkmcnt(0)
	v_add_f32_e32 v0, v0, v1
	ds_write_b32 v218, v0 offset:5648

; #define LAS __attribute__((address_space(3)))
; #define PG8_BAR __builtin_amdgcn_s_barrier()
; template <class Epi, class Sched, bool ALIGN_EPI = false, bool SP2 = false>
; __device__ __forceinline__ void gemm_phase(PG8_LAS unsigned char* lds, const Gemm g, const Sched& S, const Epi& E) {
;     ...
;         if constexpr (ALIGN_EPI) { if (wr == 0) PG8_BAR; }
;         if constexpr (!Epi::AFTER_DRAIN) { E(acc, cur, wr, wc, fr, fq); S.done(cur); }
;         if (!has_next) break;
;         if (!(TwoSeg<Epi>::v && cur.seg == 0)) {
; #pragma unroll
;         for (int a = 0; a < 2; ++a)
; #pragma unroll
;             for (int b = 0; b < 2; ++b)
; #pragma unroll
;                 for (int m = 0; m < 4; ++m)
; #pragma unroll
;                     for (int n = 0; n < 2; ++n) acc[a][b][m][n] = (f32x4){0.f, 0.f, 0.f, 0.f};
;         }
;         cur = nxt; cA = nA; cB = nB; ++ui;
;         if constexpr (ALIGN_EPI) { if (wr == 1) PG8_BAR; }
;     __device__ __forceinline__ void operator()(const pg8::f32x4 (&acc)[2][2][4][2], const pg8::Unit& u, int wr, int wc, int fr, int fq) const {
;         LAS char* xl = (LAS char*)xb + ((wr * 64 + fr) * 8 + wc) * 4; asm volatile("" : "+v"(xl));
;         const int b = u.pm >> 4; const float* mb = e.mod + (size_t)b * NMOD;
; #pragma unroll
;         for (int bj = 0; bj < 2; ++bj) {
;             const int c0 = u.pn * 256 + bj * 128 + wc * 32 + 8 * fq; float g1[8], gm[8];
; #pragma unroll
;             for (int h = 0; h < 2; ++h) { const f32x4 a = *(const f32x4*)(mb + 2 * DM + c0 + 4 * h), sc = *(const f32x4*)(mb + 4 * DM + c0 + 4 * h), ng = *(const f32x4*)(e.n2g + c0 + 4 * h);
; #pragma unroll
;                 for (int i = 0; i < 4; ++i) { g1[4 * h + i] = a[i]; gm[4 * h + i] = ng[i] * (1.0f + sc[i]); } }
; #pragma unroll
;             for (int ai = 0; ai < 2; ++ai) {
;                 f32x4 xa[4], xc[4];
; #pragma unroll
;                 for (int m = 0; m < 4; ++m) { const size_t off = (size_t)(u.pm * 256 + ai * 128 + wr * 64 + m * 16 + fr) * DM + c0; xa[m] = __builtin_nontemporal_load((const f32x4*)(e.x + off)); xc[m] = __builtin_nontemporal_load((const f32x4*)(e.x + off + 4)); }
; #pragma unroll
;                 for (int m = 0; m < 4; ++m) { ACC8(v, ai, bj, m); const size_t off = (size_t)(u.pm * 256 + ai * 128 + wr * 64 + m * 16 + fr) * DM + c0;
;                     float o[8], y[8], s = 0.f;
; #pragma unroll
.LBB9_702:
	s_or_b64 exec, exec, s[2:3]
	s_andn2_b64 vcc, exec, s[6:7]
	s_mov_b64 s[2:3], -1
	s_cbranch_vccnz .LBB9_657
	s_andn2_b64 vcc, exec, s[12:13]
	s_cbranch_vccnz .LBB9_656
	s_barrier
	s_branch .LBB9_656
.Lp5o_668:
	s_ashr_i32 s2, s30, 4
	s_mul_hi_i32 s3, s2, 0x6000
	s_mulk_i32 s2, 0x6000
	s_add_u32 s2, s48, s2
	s_addc_u32 s3, s49, s3
	s_add_u32 s34, s2, 0x2000
	s_addc_u32 s35, s3, 0
	s_add_u32 s36, s2, 0x4000
	v_lshl_or_b32 v176, s10, 8, v211
	s_addc_u32 s37, s3, 0
	s_lshl_b32 s11, s30, 8
	v_add_u32_e32 v198, s11, v209
	v_ashrrev_i32_e32 v177, 31, v176
	v_readlane_b32 s60, v251, 0
	v_lshlrev_b64 v[128:129], 2, v[176:177]
	v_readlane_b32 s61, v251, 1
	v_readlane_b32 s74, v251, 14
	v_readlane_b32 s75, v251, 15
	v_ashrrev_i32_e32 v199, 31, v198
	v_mov_b32_e32 v218, v212
	v_lshl_add_u64 v[130:131], s[34:35], 0, v[128:129]
	v_lshl_add_u64 v[132:133], s[36:37], 0, v[128:129]
	v_lshl_add_u64 v[178:179], s[74:75], 0, v[128:129]
	v_lshl_add_u64 v[200:201], s[60:61], 0, v[128:129]
	v_lshlrev_b64 v[128:129], 12, v[198:199]
	global_load_dwordx4 v[190:193], v[132:133], off offset:16
	global_load_dwordx4 v[194:197], v[132:133], off
	global_load_dwordx4 v[222:225], v[178:179], off offset:16
	global_load_dwordx4 v[226:229], v[178:179], off
	v_lshl_add_u64 v[182:183], v[200:201], 0, v[128:129]
	global_load_dwordx4 v[230:233], v[182:183], off nt
	global_load_dwordx4 v[132:135], v[130:131], off
	s_nop 0
	global_load_dwordx4 v[128:131], v[130:131], off offset:16
	s_nop 0
	global_load_dwordx4 v[234:237], v[182:183], off offset:16 nt
	v_or_b32_e32 v206, 16, v198
	v_or_b32_e32 v204, 32, v198
	v_or_b32_e32 v202, 48, v198
	v_ashrrev_i32_e32 v207, 31, v206
	v_ashrrev_i32_e32 v205, 31, v204
	v_ashrrev_i32_e32 v203, 31, v202
	v_lshlrev_b64 v[136:137], 12, v[206:207]
	v_lshlrev_b64 v[138:139], 12, v[204:205]
	v_lshlrev_b64 v[140:141], 12, v[202:203]
	v_lshl_add_u64 v[188:189], v[200:201], 0, v[136:137]
	v_lshl_add_u64 v[186:187], v[200:201], 0, v[138:139]
	v_lshl_add_u64 v[184:185], v[200:201], 0, v[140:141]
	global_load_dwordx4 v[152:155], v[188:189], off offset:16 nt
	global_load_dwordx4 v[156:159], v[188:189], off nt
	global_load_dwordx4 v[144:147], v[186:187], off offset:16 nt
	global_load_dwordx4 v[148:151], v[186:187], off nt
	global_load_dwordx4 v[136:139], v[184:185], off offset:16 nt
	global_load_dwordx4 v[140:143], v[184:185], off nt
	v_and_b32_e32 v181, 64, v217
	v_xor_b32_e32 v180, 16, v217
	v_add_u32_e32 v181, 64, v181
	v_cmp_lt_i32_e32 vcc, v180, v181
	v_xor_b32_e32 v219, 32, v217
	v_readlane_b32 s62, v251, 2
	v_cndmask_b32_e32 v180, v217, v180, vcc
	v_lshlrev_b32_e32 v220, 2, v180
	v_cmp_lt_i32_e32 vcc, v219, v181
	v_readlane_b32 s63, v251, 3
	v_readlane_b32 s64, v251, 4
	v_cndmask_b32_e32 v181, v217, v219, vcc
	v_lshlrev_b32_e32 v219, 2, v181
	v_lshlrev_b64 v[180:181], 10, v[198:199]
	v_lshl_add_u64 v[238:239], v[180:181], 0, v[176:177]
	v_readlane_b32 s65, v251, 5
	v_readlane_b32 s66, v251, 6
	v_readlane_b32 s67, v251, 7
	v_readlane_b32 s68, v251, 8
	v_readlane_b32 s69, v251, 9
	v_readlane_b32 s70, v251, 10
	v_readlane_b32 s71, v251, 11
	v_readlane_b32 s72, v251, 12
	v_readlane_b32 s73, v251, 13
	s_waitcnt vmcnt(0)
	v_pk_add_f32 v[190:191], v[190:191], 1.0 op_sel_hi:[1,0]
	v_pk_add_f32 v[192:193], v[192:193], 1.0 op_sel_hi:[1,0]
	v_pk_mul_f32 v[190:191], v[222:223], v[190:191]
	v_pk_fma_f32 v[222:223], v[124:125], v[132:133], v[230:231]
	v_pk_mul_f32 v[192:193], v[224:225], v[192:193]
	v_pk_fma_f32 v[224:225], v[126:127], v[134:135], v[232:233]
	v_pk_mul_f32 v[126:127], v[222:223], v[222:223]
	v_pk_mul_f32 v[124:125], v[224:225], v[224:225]
	v_add_f32_e32 v126, v126, v127
	v_pk_fma_f32 v[120:121], v[120:121], v[128:129], v[234:235]
	v_add_f32_e32 v124, v124, v126
	v_pk_mul_f32 v[232:233], v[120:121], v[120:121]
	v_add_f32_e32 v124, v125, v124
	v_pk_fma_f32 v[122:123], v[122:123], v[130:131], v[236:237]
	v_add_f32_e32 v124, v232, v124
	v_pk_mul_f32 v[230:231], v[122:123], v[122:123]
	v_add_f32_e32 v124, v233, v124
	v_add_f32_e32 v124, v230, v124
	v_add_f32_e32 v124, v231, v124
	ds_bpermute_b32 v125, v220, v124
	v_lshl_add_u64 v[126:127], v[238:239], 2, s[88:89]
	v_pk_mul_f32 v[234:235], v[190:191], v[120:121]
	global_store_dwordx4 v[126:127], v[222:225], off
	global_store_dwordx4 v[126:127], v[120:123], off offset:16
	v_pk_add_f32 v[194:195], v[194:195], 1.0 op_sel_hi:[1,0]
	v_pk_add_f32 v[196:197], v[196:197], 1.0 op_sel_hi:[1,0]
	s_waitcnt lgkmcnt(0)
	v_add_f32_e32 v120, v124, v125
	ds_bpermute_b32 v121, v219, v120
	v_pk_mul_f32 v[194:195], v[226:227], v[194:195]
	v_pk_mul_f32 v[196:197], v[228:229], v[196:197]
	v_pk_mul_f32 v[226:227], v[194:195], v[222:223]
	v_pk_mul_f32 v[228:229], v[196:197], v[224:225]
	v_pk_mul_f32 v[236:237], v[192:193], v[122:123]
	v_cvt_pk_bf16_f32 v122, v226, v227
	v_cvt_pk_bf16_f32 v123, v228, v229
	v_cvt_pk_bf16_f32 v124, v234, v235
	v_cvt_pk_bf16_f32 v125, v236, v237
	v_lshl_add_u64 v[222:223], v[238:239], 1, s[16:17]
	global_store_dwordx4 v[222:223], v[122:125], off
	s_and_saveexec_b64 s[2:3], s[0:1]
	s_cbranch_execz .Lp5o_670
	s_waitcnt lgkmcnt(0)
	v_add_f32_e32 v120, v120, v121
	ds_write_b32 v218, v120

; #define LAS __attribute__((address_space(3)))
; #define LDS_WAIT() asm volatile("s_waitcnt lgkmcnt(0)" ::: "memory")
;     __device__ __forceinline__ void operator()(const pg8::f32x4 (&acc)[2][2][4][2], const pg8::Unit& u, int wr, int wc, int fr, int fq) const {
;     ...
;         LDS_WAIT(); __builtin_amdgcn_s_barrier(); asm volatile("" ::: "memory");
;         const int t = threadIdx.x;
;         if (t < 256) { LAS char* xr = (LAS char*)xb + t * 32; asm volatile("" : "+v"(xr)); const f32x4 a = *(const LAS f32x4*)xr, b2 = *(const LAS f32x4*)(xr + 16);
;             SSQ[(size_t)(u.pm * 256 + t) * 4 + u.pn] = ((a[0] + a[1]) + (a[2] + a[3])) + ((b2[0] + b2[1]) + (b2[2] + b2[3])); }
.Lp5o_700:
	s_or_b64 exec, exec, s[2:3]
	s_waitcnt lgkmcnt(0)
	s_barrier
	s_and_saveexec_b64 s[2:3], s[4:5]
	s_cbranch_execz .LBB9_702
	v_mov_b32_e32 v4, v213
	s_waitcnt lgkmcnt(0)
	ds_read_b128 v[0:3], v4
	ds_read_b128 v[4:7], v4 offset:16
	s_waitcnt lgkmcnt(1)
	v_mov_b32_e32 v8, v0
	s_waitcnt lgkmcnt(0)
	v_mov_b32_e32 v9, v4
	v_mov_b32_e32 v4, v1
	v_mov_b32_e32 v0, v2
	v_mov_b32_e32 v1, v6
	v_mov_b32_e32 v6, v3
	v_pk_add_f32 v[4:5], v[8:9], v[4:5]
	v_pk_add_f32 v[0:1], v[0:1], v[6:7]
	s_nop 0
	v_pk_add_f32 v[0:1], v[4:5], v[0:1]
	s_nop 0
	v_add_f32_e32 v2, v0, v1
	v_or_b32_e32 v0, s11, v208
	v_ashrrev_i32_e32 v1, 31, v0
	s_ashr_i32 s11, s10, 31
	v_lshl_add_u64 v[0:1], v[0:1], 4, s[14:15]
	v_lshl_add_u64 v[0:1], s[10:11], 2, v[0:1]
	global_store_dword v[0:1], v2, off
	s_branch .LBB9_702
